# RWKV scan: empty reduce-scatter slots carry the last LDS reads of the step instead of filler nops
# speedup vs baseline: 1.0112x; 1.0029x over previous
.Lscan_chunk:
	ds_read_b128 v[96:99], v139 offset:3456
	ds_read_b32 v104, v140 offset:2688
	ds_read_b128 v[88:91], v139 offset:2944
	ds_read_b128 v[84:87], v139 offset:2688
	ds_read_b128 v[92:95], v139 offset:3200
	v_pk_mul_f32 v[16:17], v[0:1], v[44:45]
	v_pk_fma_f32 v[16:17], v[2:3], v[46:47], v[16:17]
	v_add_f32_e32 v18, v16, v17
	v_pk_mul_f32 v[20:21], v[0:1], v[122:123]
	v_pk_fma_f32 v[4:5], v[0:1], v[40:41], v[8:9]
	v_add_f32_dpp v18, v18, v18 quad_perm:[1,0,3,2] row_mask:0xf bank_mask:0xf bound_ctrl:1
	v_pk_fma_f32 v[20:21], v[2:3], v[124:125], v[20:21]
	v_add_f32_e32 v201, v20, v21
	v_add_f32_dpp v18, v18, v18 quad_perm:[2,3,0,1] row_mask:0xf bank_mask:0xf bound_ctrl:1
	ds_read_b128 v[100:103], v139 offset:3712
	v_pk_fma_f32 v[6:7], v[2:3], v[42:43], v[10:11]
	v_add_f32_dpp v18, v18, v18 row_half_mirror row_mask:0xf bank_mask:0xf bound_ctrl:1
	v_add_f32_dpp v201, v201, v201 row_ror:8 row_mask:0xf bank_mask:0xc bound_ctrl:1
	v_add_f32_dpp v201, v191, v191 row_ror:8 row_mask:0xf bank_mask:0x3 bound_ctrl:1
	v_add_f32_dpp v18, v18, v18 row_ror:8 row_mask:0xf bank_mask:0xf bound_ctrl:1
	v_pk_fma_f32 v[0:1], v[48:49], v[18:19], v[4:5] op_sel_hi:[1,0,1] neg_lo:[1,0,0] neg_hi:[1,0,0]
	v_pk_fma_f32 v[2:3], v[50:51], v[18:19], v[6:7] op_sel_hi:[1,0,1] neg_lo:[1,0,0] neg_hi:[1,0,0]
	s_waitcnt lgkmcnt(6)
	v_pk_mul_f32 v[8:9], v[74:75], v[82:83] op_sel_hi:[1,0]
	v_pk_mul_f32 v[10:11], v[76:77], v[82:83] op_sel_hi:[1,0]
	ds_read_b128 v[118:121], v139 offset:4800
	ds_read_b32 v126, v140 offset:4032
	ds_read_b128 v[110:113], v139 offset:4288
	ds_read_b128 v[106:109], v139 offset:4032
	ds_read_b128 v[114:117], v139 offset:4544
	ds_read_b128 v[122:125], v139 offset:5056
	v_pk_mul_f32 v[16:17], v[0:1], v[66:67]
	v_pk_fma_f32 v[16:17], v[2:3], v[68:69], v[16:17]
	v_add_f32_e32 v18, v16, v17
	v_pk_mul_f32 v[20:21], v[0:1], v[56:57]
	v_pk_fma_f32 v[4:5], v[0:1], v[62:63], v[8:9]
	v_add_f32_dpp v18, v18, v18 quad_perm:[1,0,3,2] row_mask:0xf bank_mask:0xf bound_ctrl:1
	v_pk_fma_f32 v[20:21], v[2:3], v[58:59], v[20:21]
	v_add_f32_e32 v12, v20, v21
	v_add_f32_dpp v18, v18, v18 quad_perm:[2,3,0,1] row_mask:0xf bank_mask:0xf bound_ctrl:1
	v_add_f32_dpp v196, v196, v196 row_half_mirror row_mask:0xf bank_mask:0xa bound_ctrl:1
	v_pk_fma_f32 v[6:7], v[2:3], v[64:65], v[10:11]
	v_add_f32_dpp v18, v18, v18 row_half_mirror row_mask:0xf bank_mask:0xf bound_ctrl:1
	v_add_f32_dpp v196, v192, v192 row_half_mirror row_mask:0xf bank_mask:0x5 bound_ctrl:1
	v_add_f32_dpp v197, v197, v197 row_half_mirror row_mask:0xf bank_mask:0xa bound_ctrl:1
	v_add_f32_dpp v18, v18, v18 row_ror:8 row_mask:0xf bank_mask:0xf bound_ctrl:1
	v_pk_fma_f32 v[0:1], v[70:71], v[18:19], v[4:5] op_sel_hi:[1,0,1] neg_lo:[1,0,0] neg_hi:[1,0,0]
	v_pk_fma_f32 v[2:3], v[72:73], v[18:19], v[6:7] op_sel_hi:[1,0,1] neg_lo:[1,0,0] neg_hi:[1,0,0]
	s_waitcnt lgkmcnt(6)
	v_pk_mul_f32 v[8:9], v[96:97], v[104:105] op_sel_hi:[1,0]
	v_pk_mul_f32 v[10:11], v[98:99], v[104:105] op_sel_hi:[1,0]
	ds_read_b128 v[52:55], v139 offset:6144
	ds_read_b32 v60, v140 offset:5376
	ds_read_b128 v[44:47], v139 offset:5632
	ds_read_b128 v[40:43], v139 offset:5376
	ds_read_b128 v[48:51], v139 offset:5888
	ds_read_b128 v[56:59], v139 offset:6400
	v_pk_mul_f32 v[16:17], v[0:1], v[88:89]
	v_pk_fma_f32 v[16:17], v[2:3], v[90:91], v[16:17]
	v_add_f32_e32 v18, v16, v17
	v_pk_mul_f32 v[20:21], v[0:1], v[78:79]
	v_pk_fma_f32 v[4:5], v[0:1], v[84:85], v[8:9]
	v_add_f32_dpp v18, v18, v18 quad_perm:[1,0,3,2] row_mask:0xf bank_mask:0xf bound_ctrl:1
	v_pk_fma_f32 v[20:21], v[2:3], v[80:81], v[20:21]
	v_add_f32_e32 v13, v20, v21
	v_add_f32_dpp v18, v18, v18 quad_perm:[2,3,0,1] row_mask:0xf bank_mask:0xf bound_ctrl:1
	v_add_f32_dpp v197, v193, v193 row_half_mirror row_mask:0xf bank_mask:0x5 bound_ctrl:1
	v_pk_fma_f32 v[6:7], v[2:3], v[86:87], v[10:11]
	v_add_f32_dpp v18, v18, v18 row_half_mirror row_mask:0xf bank_mask:0xf bound_ctrl:1
	v_add_f32_dpp v200, v200, v200 row_half_mirror row_mask:0xf bank_mask:0xa bound_ctrl:1
	v_add_f32_dpp v200, v194, v194 row_half_mirror row_mask:0xf bank_mask:0x5 bound_ctrl:1
	v_add_f32_dpp v18, v18, v18 row_ror:8 row_mask:0xf bank_mask:0xf bound_ctrl:1
	v_pk_fma_f32 v[0:1], v[92:93], v[18:19], v[4:5] op_sel_hi:[1,0,1] neg_lo:[1,0,0] neg_hi:[1,0,0]
	v_pk_fma_f32 v[2:3], v[94:95], v[18:19], v[6:7] op_sel_hi:[1,0,1] neg_lo:[1,0,0] neg_hi:[1,0,0]
	s_waitcnt lgkmcnt(6)
	v_pk_mul_f32 v[8:9], v[118:119], v[126:127] op_sel_hi:[1,0]
	v_pk_mul_f32 v[10:11], v[120:121], v[126:127] op_sel_hi:[1,0]
	ds_read_b128 v[74:77], v139 offset:7488
	ds_read_b32 v82, v140 offset:6720
	ds_read_b128 v[66:69], v139 offset:6976
	ds_read_b128 v[62:65], v139 offset:6720
	ds_read_b128 v[70:73], v139 offset:7232
	ds_read_b128 v[78:81], v139 offset:7744
	v_pk_mul_f32 v[16:17], v[0:1], v[110:111]
	v_pk_fma_f32 v[16:17], v[2:3], v[112:113], v[16:17]
	v_add_f32_e32 v18, v16, v17
	v_pk_mul_f32 v[20:21], v[0:1], v[100:101]
	v_pk_fma_f32 v[4:5], v[0:1], v[106:107], v[8:9]
	v_add_f32_dpp v18, v18, v18 quad_perm:[1,0,3,2] row_mask:0xf bank_mask:0xf bound_ctrl:1
	v_pk_fma_f32 v[20:21], v[2:3], v[102:103], v[20:21]
	v_add_f32_e32 v14, v20, v21
	v_add_f32_dpp v18, v18, v18 quad_perm:[2,3,0,1] row_mask:0xf bank_mask:0xf bound_ctrl:1
	v_add_f32_dpp v201, v201, v201 row_half_mirror row_mask:0xf bank_mask:0xa bound_ctrl:1
	v_pk_fma_f32 v[6:7], v[2:3], v[108:109], v[10:11]
	v_add_f32_dpp v18, v18, v18 row_half_mirror row_mask:0xf bank_mask:0xf bound_ctrl:1
	v_add_f32_dpp v201, v195, v195 row_half_mirror row_mask:0xf bank_mask:0x5 bound_ctrl:1
	v_cndmask_b32_e64 v22, v196, v200, s[36:37]
	v_add_f32_dpp v18, v18, v18 row_ror:8 row_mask:0xf bank_mask:0xf bound_ctrl:1
	v_pk_fma_f32 v[0:1], v[114:115], v[18:19], v[4:5] op_sel_hi:[1,0,1] neg_lo:[1,0,0] neg_hi:[1,0,0]
	v_pk_fma_f32 v[2:3], v[116:117], v[18:19], v[6:7] op_sel_hi:[1,0,1] neg_lo:[1,0,0] neg_hi:[1,0,0]
	s_waitcnt lgkmcnt(6)
	v_pk_mul_f32 v[8:9], v[52:53], v[60:61] op_sel_hi:[1,0]
	v_pk_mul_f32 v[10:11], v[54:55], v[60:61] op_sel_hi:[1,0]
	ds_read_b128 v[96:99], v139 offset:8832
	ds_read_b32 v104, v140 offset:8064
	ds_read_b128 v[88:91], v139 offset:8320
	ds_read_b128 v[84:87], v139 offset:8064
	ds_read_b128 v[92:95], v139 offset:8576
	ds_read_b128 v[100:103], v139 offset:9088
	v_pk_mul_f32 v[16:17], v[0:1], v[44:45]
	v_pk_fma_f32 v[16:17], v[2:3], v[46:47], v[16:17]
	v_add_f32_e32 v18, v16, v17
	v_pk_mul_f32 v[20:21], v[0:1], v[122:123]
	v_pk_fma_f32 v[4:5], v[0:1], v[40:41], v[8:9]
	v_add_f32_dpp v18, v18, v18 quad_perm:[1,0,3,2] row_mask:0xf bank_mask:0xf bound_ctrl:1
	v_pk_fma_f32 v[20:21], v[2:3], v[124:125], v[20:21]
	v_add_f32_e32 v15, v20, v21
	v_add_f32_dpp v18, v18, v18 quad_perm:[2,3,0,1] row_mask:0xf bank_mask:0xf bound_ctrl:1
	v_cndmask_b32_e64 v202, v200, v196, s[36:37]
	v_pk_fma_f32 v[6:7], v[2:3], v[42:43], v[10:11]
	v_add_f32_dpp v18, v18, v18 row_half_mirror row_mask:0xf bank_mask:0xf bound_ctrl:1
	v_add_f32_dpp v200, v202, v22 quad_perm:[2,3,0,1] row_mask:0xf bank_mask:0xf bound_ctrl:1
	v_cndmask_b32_e64 v203, v197, v201, s[36:37]
	v_add_f32_dpp v18, v18, v18 row_ror:8 row_mask:0xf bank_mask:0xf bound_ctrl:1
	v_pk_fma_f32 v[0:1], v[48:49], v[18:19], v[4:5] op_sel_hi:[1,0,1] neg_lo:[1,0,0] neg_hi:[1,0,0]
	v_pk_fma_f32 v[2:3], v[50:51], v[18:19], v[6:7] op_sel_hi:[1,0,1] neg_lo:[1,0,0] neg_hi:[1,0,0]
	s_waitcnt lgkmcnt(6)
	v_pk_mul_f32 v[8:9], v[74:75], v[82:83] op_sel_hi:[1,0]
	v_pk_mul_f32 v[10:11], v[76:77], v[82:83] op_sel_hi:[1,0]
	ds_read_b128 v[118:121], v139 offset:10176
	ds_read_b32 v126, v140 offset:9408
	ds_read_b128 v[110:113], v139 offset:9664
	ds_read_b128 v[106:109], v139 offset:9408
	ds_read_b128 v[114:117], v139 offset:9920
	ds_read_b128 v[122:125], v139 offset:10432
	v_pk_mul_f32 v[16:17], v[0:1], v[66:67]
	v_pk_fma_f32 v[16:17], v[2:3], v[68:69], v[16:17]
	v_add_f32_e32 v18, v16, v17
	v_pk_mul_f32 v[20:21], v[0:1], v[56:57]
	v_pk_fma_f32 v[4:5], v[0:1], v[62:63], v[8:9]
	v_add_f32_dpp v18, v18, v18 quad_perm:[1,0,3,2] row_mask:0xf bank_mask:0xf bound_ctrl:1
	v_pk_fma_f32 v[20:21], v[2:3], v[58:59], v[20:21]
	v_add_f32_e32 v188, v20, v21
	v_add_f32_dpp v18, v18, v18 quad_perm:[2,3,0,1] row_mask:0xf bank_mask:0xf bound_ctrl:1
	v_cndmask_b32_e64 v202, v201, v197, s[36:37]
	v_pk_fma_f32 v[6:7], v[2:3], v[64:65], v[10:11]
	v_add_f32_dpp v18, v18, v18 row_half_mirror row_mask:0xf bank_mask:0xf bound_ctrl:1
	v_add_f32_dpp v201, v202, v203 quad_perm:[2,3,0,1] row_mask:0xf bank_mask:0xf bound_ctrl:1
	v_cndmask_b32_e64 v22, v200, v201, s[38:39]
	v_add_f32_dpp v18, v18, v18 row_ror:8 row_mask:0xf bank_mask:0xf bound_ctrl:1
	v_pk_fma_f32 v[0:1], v[70:71], v[18:19], v[4:5] op_sel_hi:[1,0,1] neg_lo:[1,0,0] neg_hi:[1,0,0]
	v_pk_fma_f32 v[2:3], v[72:73], v[18:19], v[6:7] op_sel_hi:[1,0,1] neg_lo:[1,0,0] neg_hi:[1,0,0]
	s_waitcnt lgkmcnt(6)
	v_pk_mul_f32 v[8:9], v[96:97], v[104:105] op_sel_hi:[1,0]
	v_pk_mul_f32 v[10:11], v[98:99], v[104:105] op_sel_hi:[1,0]
	ds_read_b128 v[52:55], v139 offset:11520
	ds_read_b32 v60, v140 offset:10752
	ds_read_b128 v[44:47], v139 offset:11008
	ds_read_b128 v[40:43], v139 offset:10752
	ds_read_b128 v[48:51], v139 offset:11264
	v_pk_mul_f32 v[16:17], v[0:1], v[88:89]
	v_pk_fma_f32 v[16:17], v[2:3], v[90:91], v[16:17]
	v_add_f32_e32 v18, v16, v17
	v_pk_mul_f32 v[20:21], v[0:1], v[78:79]
	v_pk_fma_f32 v[4:5], v[0:1], v[84:85], v[8:9]
	v_add_f32_dpp v18, v18, v18 quad_perm:[1,0,3,2] row_mask:0xf bank_mask:0xf bound_ctrl:1
	v_pk_fma_f32 v[20:21], v[2:3], v[80:81], v[20:21]
	v_add_f32_e32 v189, v20, v21
	v_add_f32_dpp v18, v18, v18 quad_perm:[2,3,0,1] row_mask:0xf bank_mask:0xf bound_ctrl:1
	v_cndmask_b32_e64 v202, v201, v200, s[38:39]
	v_pk_fma_f32 v[6:7], v[2:3], v[86:87], v[10:11]
	v_add_f32_dpp v18, v18, v18 row_half_mirror row_mask:0xf bank_mask:0xf bound_ctrl:1
	v_add_f32_dpp v23, v202, v22 quad_perm:[1,0,3,2] row_mask:0xf bank_mask:0xf bound_ctrl:1
	ds_read_b128 v[56:59], v139 offset:11776
	v_add_f32_dpp v18, v18, v18 row_ror:8 row_mask:0xf bank_mask:0xf bound_ctrl:1
	v_pk_fma_f32 v[0:1], v[92:93], v[18:19], v[4:5] op_sel_hi:[1,0,1] neg_lo:[1,0,0] neg_hi:[1,0,0]
	v_pk_fma_f32 v[2:3], v[94:95], v[18:19], v[6:7] op_sel_hi:[1,0,1] neg_lo:[1,0,0] neg_hi:[1,0,0]
	s_waitcnt lgkmcnt(6)
	v_pk_mul_f32 v[8:9], v[118:119], v[126:127] op_sel_hi:[1,0]
	v_pk_mul_f32 v[10:11], v[120:121], v[126:127] op_sel_hi:[1,0]
	s_cmp_eq_u32 s4, 0
	s_cbranch_scc1 .Lscan_noy0
	global_store_dword v138, v23, s[96:97]
	v_add_u32_e32 v138, s90, v138
.Lscan_noy0:
	ds_read_b128 v[74:77], v139 offset:12864
	ds_read_b32 v82, v140 offset:12096
	ds_read_b128 v[66:69], v139 offset:12352
	v_pk_mul_f32 v[16:17], v[0:1], v[110:111]
	v_pk_fma_f32 v[16:17], v[2:3], v[112:113], v[16:17]
	v_add_f32_e32 v18, v16, v17
	v_pk_mul_f32 v[20:21], v[0:1], v[100:101]
	v_pk_fma_f32 v[4:5], v[0:1], v[106:107], v[8:9]
	v_add_f32_dpp v18, v18, v18 quad_perm:[1,0,3,2] row_mask:0xf bank_mask:0xf bound_ctrl:1
	v_pk_fma_f32 v[20:21], v[2:3], v[102:103], v[20:21]
	v_add_f32_e32 v190, v20, v21
	v_add_f32_dpp v18, v18, v18 quad_perm:[2,3,0,1] row_mask:0xf bank_mask:0xf bound_ctrl:1
	ds_read_b128 v[62:65], v139 offset:12096
	v_pk_fma_f32 v[6:7], v[2:3], v[108:109], v[10:11]
	v_add_f32_dpp v18, v18, v18 row_half_mirror row_mask:0xf bank_mask:0xf bound_ctrl:1
	ds_read_b128 v[70:73], v139 offset:12608
	ds_read_b128 v[78:81], v139 offset:13120
	v_add_f32_dpp v18, v18, v18 row_ror:8 row_mask:0xf bank_mask:0xf bound_ctrl:1
	v_pk_fma_f32 v[0:1], v[114:115], v[18:19], v[4:5] op_sel_hi:[1,0,1] neg_lo:[1,0,0] neg_hi:[1,0,0]
	v_pk_fma_f32 v[2:3], v[116:117], v[18:19], v[6:7] op_sel_hi:[1,0,1] neg_lo:[1,0,0] neg_hi:[1,0,0]
	s_waitcnt lgkmcnt(6)
	v_pk_mul_f32 v[8:9], v[52:53], v[60:61] op_sel_hi:[1,0]
	v_pk_mul_f32 v[10:11], v[54:55], v[60:61] op_sel_hi:[1,0]
	ds_read_b128 v[96:99], v139 offset:14208
	ds_read_b32 v104, v140 offset:13440
	ds_read_b128 v[88:91], v139 offset:13696
	v_pk_mul_f32 v[16:17], v[0:1], v[44:45]
	v_pk_fma_f32 v[16:17], v[2:3], v[46:47], v[16:17]
	v_add_f32_e32 v18, v16, v17
	v_pk_mul_f32 v[20:21], v[0:1], v[122:123]
	v_pk_fma_f32 v[4:5], v[0:1], v[40:41], v[8:9]
	v_add_f32_dpp v18, v18, v18 quad_perm:[1,0,3,2] row_mask:0xf bank_mask:0xf bound_ctrl:1
	v_pk_fma_f32 v[20:21], v[2:3], v[124:125], v[20:21]
	v_add_f32_e32 v191, v20, v21
	v_add_f32_dpp v18, v18, v18 quad_perm:[2,3,0,1] row_mask:0xf bank_mask:0xf bound_ctrl:1
	ds_read_b128 v[84:87], v139 offset:13440
	v_pk_fma_f32 v[6:7], v[2:3], v[42:43], v[10:11]
	v_add_f32_dpp v18, v18, v18 row_half_mirror row_mask:0xf bank_mask:0xf bound_ctrl:1
	ds_read_b128 v[92:95], v139 offset:13952
	ds_read_b128 v[100:103], v139 offset:14464
	v_add_f32_dpp v18, v18, v18 row_ror:8 row_mask:0xf bank_mask:0xf bound_ctrl:1
	v_pk_fma_f32 v[0:1], v[48:49], v[18:19], v[4:5] op_sel_hi:[1,0,1] neg_lo:[1,0,0] neg_hi:[1,0,0]
	v_pk_fma_f32 v[2:3], v[50:51], v[18:19], v[6:7] op_sel_hi:[1,0,1] neg_lo:[1,0,0] neg_hi:[1,0,0]
	s_waitcnt lgkmcnt(6)
	v_pk_mul_f32 v[8:9], v[74:75], v[82:83] op_sel_hi:[1,0]
	v_pk_mul_f32 v[10:11], v[76:77], v[82:83] op_sel_hi:[1,0]
	ds_read_b128 v[118:121], v139 offset:15552
	ds_read_b32 v126, v140 offset:14784
	ds_read_b128 v[110:113], v139 offset:15040
	ds_read_b128 v[106:109], v139 offset:14784
	ds_read_b128 v[114:117], v139 offset:15296
	v_pk_mul_f32 v[16:17], v[0:1], v[66:67]
	v_pk_fma_f32 v[16:17], v[2:3], v[68:69], v[16:17]
	v_add_f32_e32 v18, v16, v17
	v_pk_mul_f32 v[20:21], v[0:1], v[56:57]
	v_pk_fma_f32 v[4:5], v[0:1], v[62:63], v[8:9]
	v_add_f32_dpp v18, v18, v18 quad_perm:[1,0,3,2] row_mask:0xf bank_mask:0xf bound_ctrl:1
	v_pk_fma_f32 v[20:21], v[2:3], v[58:59], v[20:21]
	v_add_f32_e32 v192, v20, v21
	v_add_f32_dpp v18, v18, v18 quad_perm:[2,3,0,1] row_mask:0xf bank_mask:0xf bound_ctrl:1
	ds_read_b128 v[122:125], v139 offset:15808
	v_pk_fma_f32 v[6:7], v[2:3], v[64:65], v[10:11]
	v_add_f32_dpp v18, v18, v18 row_half_mirror row_mask:0xf bank_mask:0xf bound_ctrl:1
	v_add_f32_dpp v192, v192, v192 row_ror:8 row_mask:0xf bank_mask:0xc bound_ctrl:1
	v_add_f32_dpp v192, v12, v12 row_ror:8 row_mask:0xf bank_mask:0x3 bound_ctrl:1
	v_add_f32_dpp v18, v18, v18 row_ror:8 row_mask:0xf bank_mask:0xf bound_ctrl:1
	v_pk_fma_f32 v[0:1], v[70:71], v[18:19], v[4:5] op_sel_hi:[1,0,1] neg_lo:[1,0,0] neg_hi:[1,0,0]
	v_pk_fma_f32 v[2:3], v[72:73], v[18:19], v[6:7] op_sel_hi:[1,0,1] neg_lo:[1,0,0] neg_hi:[1,0,0]
	s_waitcnt lgkmcnt(6)
	v_pk_mul_f32 v[8:9], v[96:97], v[104:105] op_sel_hi:[1,0]
	v_pk_mul_f32 v[10:11], v[98:99], v[104:105] op_sel_hi:[1,0]
	ds_read_b128 v[52:55], v139 offset:16896
	ds_read_b32 v60, v140 offset:16128
	ds_read_b128 v[44:47], v139 offset:16384
	ds_read_b128 v[40:43], v139 offset:16128
	ds_read_b128 v[48:51], v139 offset:16640
	v_pk_mul_f32 v[16:17], v[0:1], v[88:89]
	v_pk_fma_f32 v[16:17], v[2:3], v[90:91], v[16:17]
	v_add_f32_e32 v18, v16, v17
	v_pk_mul_f32 v[20:21], v[0:1], v[78:79]
	v_pk_fma_f32 v[4:5], v[0:1], v[84:85], v[8:9]
	v_add_f32_dpp v18, v18, v18 quad_perm:[1,0,3,2] row_mask:0xf bank_mask:0xf bound_ctrl:1
	v_pk_fma_f32 v[20:21], v[2:3], v[80:81], v[20:21]
	v_add_f32_e32 v193, v20, v21
	v_add_f32_dpp v18, v18, v18 quad_perm:[2,3,0,1] row_mask:0xf bank_mask:0xf bound_ctrl:1
	ds_read_b128 v[56:59], v139 offset:17152
	v_pk_fma_f32 v[6:7], v[2:3], v[86:87], v[10:11]
	v_add_f32_dpp v18, v18, v18 row_half_mirror row_mask:0xf bank_mask:0xf bound_ctrl:1
	v_add_f32_dpp v193, v193, v193 row_ror:8 row_mask:0xf bank_mask:0xc bound_ctrl:1
	v_add_f32_dpp v193, v13, v13 row_ror:8 row_mask:0xf bank_mask:0x3 bound_ctrl:1
	v_add_f32_dpp v18, v18, v18 row_ror:8 row_mask:0xf bank_mask:0xf bound_ctrl:1
	v_pk_fma_f32 v[0:1], v[92:93], v[18:19], v[4:5] op_sel_hi:[1,0,1] neg_lo:[1,0,0] neg_hi:[1,0,0]
	v_pk_fma_f32 v[2:3], v[94:95], v[18:19], v[6:7] op_sel_hi:[1,0,1] neg_lo:[1,0,0] neg_hi:[1,0,0]
	s_waitcnt lgkmcnt(6)
	v_pk_mul_f32 v[8:9], v[118:119], v[126:127] op_sel_hi:[1,0]
	v_pk_mul_f32 v[10:11], v[120:121], v[126:127] op_sel_hi:[1,0]
	s_add_i32 s0, s4, 2
	s_cmp_lt_u32 s0, s5
	s_cbranch_scc1 .Lscan_w6_0
	s_waitcnt vmcnt(0)
	s_branch .Lscan_wd_0

.Lscan_wd_0:
	ds_write_b128 v143, v[146:149]
	ds_write_b128 v143, v[150:153] offset:256
	ds_write_b128 v143, v[154:157] offset:512
	ds_write_b128 v143, v[158:161] offset:768
	ds_write_b128 v143, v[162:165] offset:1024
	ds_write_b32 v35, v166
	ds_read_b128 v[74:77], v139 offset:18240
	ds_read_b32 v82, v140 offset:17472
	ds_read_b128 v[66:69], v139 offset:17728
	ds_read_b128 v[62:65], v139 offset:17472
	ds_read_b128 v[70:73], v139 offset:17984
	v_pk_mul_f32 v[16:17], v[0:1], v[110:111]
	v_pk_fma_f32 v[16:17], v[2:3], v[112:113], v[16:17]
	v_add_f32_e32 v18, v16, v17
	v_pk_mul_f32 v[20:21], v[0:1], v[100:101]
	v_pk_fma_f32 v[4:5], v[0:1], v[106:107], v[8:9]
	v_add_f32_dpp v18, v18, v18 quad_perm:[1,0,3,2] row_mask:0xf bank_mask:0xf bound_ctrl:1
	v_pk_fma_f32 v[20:21], v[2:3], v[102:103], v[20:21]
	v_add_f32_e32 v194, v20, v21
	v_add_f32_dpp v18, v18, v18 quad_perm:[2,3,0,1] row_mask:0xf bank_mask:0xf bound_ctrl:1
	ds_read_b128 v[78:81], v139 offset:18496
	v_pk_fma_f32 v[6:7], v[2:3], v[108:109], v[10:11]
	v_add_f32_dpp v18, v18, v18 row_half_mirror row_mask:0xf bank_mask:0xf bound_ctrl:1
	v_add_f32_dpp v194, v194, v194 row_ror:8 row_mask:0xf bank_mask:0xc bound_ctrl:1
	v_add_f32_dpp v194, v14, v14 row_ror:8 row_mask:0xf bank_mask:0x3 bound_ctrl:1
	v_add_f32_dpp v18, v18, v18 row_ror:8 row_mask:0xf bank_mask:0xf bound_ctrl:1
	v_pk_fma_f32 v[0:1], v[114:115], v[18:19], v[4:5] op_sel_hi:[1,0,1] neg_lo:[1,0,0] neg_hi:[1,0,0]
	v_pk_fma_f32 v[2:3], v[116:117], v[18:19], v[6:7] op_sel_hi:[1,0,1] neg_lo:[1,0,0] neg_hi:[1,0,0]
	s_waitcnt lgkmcnt(6)
	v_pk_mul_f32 v[8:9], v[52:53], v[60:61] op_sel_hi:[1,0]
	v_pk_mul_f32 v[10:11], v[54:55], v[60:61] op_sel_hi:[1,0]
	ds_read_b128 v[96:99], v139 offset:19584
	ds_read_b32 v104, v140 offset:18816
	ds_read_b128 v[88:91], v139 offset:19072
	ds_read_b128 v[84:87], v139 offset:18816
	ds_read_b128 v[92:95], v139 offset:19328
	v_pk_mul_f32 v[16:17], v[0:1], v[44:45]
	v_pk_fma_f32 v[16:17], v[2:3], v[46:47], v[16:17]
	v_add_f32_e32 v18, v16, v17
	v_pk_mul_f32 v[20:21], v[0:1], v[122:123]
	v_pk_fma_f32 v[4:5], v[0:1], v[40:41], v[8:9]
	v_add_f32_dpp v18, v18, v18 quad_perm:[1,0,3,2] row_mask:0xf bank_mask:0xf bound_ctrl:1
	v_pk_fma_f32 v[20:21], v[2:3], v[124:125], v[20:21]
	v_add_f32_e32 v195, v20, v21
	v_add_f32_dpp v18, v18, v18 quad_perm:[2,3,0,1] row_mask:0xf bank_mask:0xf bound_ctrl:1
	ds_read_b128 v[100:103], v139 offset:19840
	v_pk_fma_f32 v[6:7], v[2:3], v[42:43], v[10:11]
	v_add_f32_dpp v18, v18, v18 row_half_mirror row_mask:0xf bank_mask:0xf bound_ctrl:1
	v_add_f32_dpp v195, v195, v195 row_ror:8 row_mask:0xf bank_mask:0xc bound_ctrl:1
	v_add_f32_dpp v195, v15, v15 row_ror:8 row_mask:0xf bank_mask:0x3 bound_ctrl:1
	v_add_f32_dpp v18, v18, v18 row_ror:8 row_mask:0xf bank_mask:0xf bound_ctrl:1
	v_pk_fma_f32 v[0:1], v[48:49], v[18:19], v[4:5] op_sel_hi:[1,0,1] neg_lo:[1,0,0] neg_hi:[1,0,0]
	v_pk_fma_f32 v[2:3], v[50:51], v[18:19], v[6:7] op_sel_hi:[1,0,1] neg_lo:[1,0,0] neg_hi:[1,0,0]
	s_waitcnt lgkmcnt(6)
	s_barrier
	s_add_i32 s0, s4, 3
	s_cmp_lt_u32 s0, s5
	s_cbranch_scc0 .Lscan_nold0
	s_mul_i32 s92, s0, s90
	v_add_u32_e32 v132, s92, v28
	v_add_u32_e32 v133, s92, v29
	v_add_u32_e32 v134, s92, v30
	v_add_u32_e32 v135, s92, v31
	v_add_u32_e32 v136, s92, v32
	v_add_u32_e32 v137, s92, v33
	global_load_dwordx4 v[146:149], v132, s[96:97]
	global_load_dwordx4 v[150:153], v133, s[96:97]
	global_load_dwordx4 v[154:157], v134, s[96:97]
	global_load_dwordx4 v[158:161], v135, s[96:97]
	global_load_dwordx4 v[162:165], v136, s[96:97]
	global_load_dword v166, v137, s[96:97]
.Lscan_nold0:
	v_pk_mul_f32 v[8:9], v[74:75], v[82:83] op_sel_hi:[1,0]
	v_pk_mul_f32 v[10:11], v[76:77], v[82:83] op_sel_hi:[1,0]
	ds_read_b128 v[118:121], v139 offset:20928
	ds_read_b32 v126, v140 offset:20160
	ds_read_b128 v[110:113], v139 offset:20416
	ds_read_b128 v[106:109], v139 offset:20160
	ds_read_b128 v[114:117], v139 offset:20672
	v_pk_mul_f32 v[16:17], v[0:1], v[66:67]
	v_pk_fma_f32 v[16:17], v[2:3], v[68:69], v[16:17]
	v_add_f32_e32 v18, v16, v17
	v_pk_mul_f32 v[20:21], v[0:1], v[56:57]
	v_pk_fma_f32 v[4:5], v[0:1], v[62:63], v[8:9]
	v_add_f32_dpp v18, v18, v18 quad_perm:[1,0,3,2] row_mask:0xf bank_mask:0xf bound_ctrl:1
	v_pk_fma_f32 v[20:21], v[2:3], v[58:59], v[20:21]
	v_add_f32_e32 v196, v20, v21
	v_add_f32_dpp v18, v18, v18 quad_perm:[2,3,0,1] row_mask:0xf bank_mask:0xf bound_ctrl:1
	ds_read_b128 v[122:125], v139 offset:21184
	v_pk_fma_f32 v[6:7], v[2:3], v[64:65], v[10:11]
	v_add_f32_dpp v18, v18, v18 row_half_mirror row_mask:0xf bank_mask:0xf bound_ctrl:1
	v_add_f32_dpp v196, v196, v196 row_ror:8 row_mask:0xf bank_mask:0xc bound_ctrl:1
	v_add_f32_dpp v196, v188, v188 row_ror:8 row_mask:0xf bank_mask:0x3 bound_ctrl:1
	v_add_f32_dpp v18, v18, v18 row_ror:8 row_mask:0xf bank_mask:0xf bound_ctrl:1
	v_pk_fma_f32 v[0:1], v[70:71], v[18:19], v[4:5] op_sel_hi:[1,0,1] neg_lo:[1,0,0] neg_hi:[1,0,0]
	v_pk_fma_f32 v[2:3], v[72:73], v[18:19], v[6:7] op_sel_hi:[1,0,1] neg_lo:[1,0,0] neg_hi:[1,0,0]
	s_waitcnt lgkmcnt(6)
	v_pk_mul_f32 v[8:9], v[96:97], v[104:105] op_sel_hi:[1,0]
	v_pk_mul_f32 v[10:11], v[98:99], v[104:105] op_sel_hi:[1,0]
	ds_read_b128 v[52:55], v141 offset:768
	ds_read_b32 v60, v142 offset:0
	ds_read_b128 v[44:47], v141 offset:256
	ds_read_b128 v[40:43], v141 offset:0
	ds_read_b128 v[48:51], v141 offset:512
	v_pk_mul_f32 v[16:17], v[0:1], v[88:89]
	v_pk_fma_f32 v[16:17], v[2:3], v[90:91], v[16:17]
	v_add_f32_e32 v18, v16, v17
	v_pk_mul_f32 v[20:21], v[0:1], v[78:79]
	v_pk_fma_f32 v[4:5], v[0:1], v[84:85], v[8:9]
	v_add_f32_dpp v18, v18, v18 quad_perm:[1,0,3,2] row_mask:0xf bank_mask:0xf bound_ctrl:1
	v_pk_fma_f32 v[20:21], v[2:3], v[80:81], v[20:21]
	v_add_f32_e32 v197, v20, v21
	v_add_f32_dpp v18, v18, v18 quad_perm:[2,3,0,1] row_mask:0xf bank_mask:0xf bound_ctrl:1
	ds_read_b128 v[56:59], v141 offset:1024
	v_pk_fma_f32 v[6:7], v[2:3], v[86:87], v[10:11]
	v_add_f32_dpp v18, v18, v18 row_half_mirror row_mask:0xf bank_mask:0xf bound_ctrl:1
	v_add_f32_dpp v197, v197, v197 row_ror:8 row_mask:0xf bank_mask:0xc bound_ctrl:1
	v_add_f32_dpp v197, v189, v189 row_ror:8 row_mask:0xf bank_mask:0x3 bound_ctrl:1
	v_add_f32_dpp v18, v18, v18 row_ror:8 row_mask:0xf bank_mask:0xf bound_ctrl:1
	v_pk_fma_f32 v[0:1], v[92:93], v[18:19], v[4:5] op_sel_hi:[1,0,1] neg_lo:[1,0,0] neg_hi:[1,0,0]
	v_pk_fma_f32 v[2:3], v[94:95], v[18:19], v[6:7] op_sel_hi:[1,0,1] neg_lo:[1,0,0] neg_hi:[1,0,0]
	s_waitcnt lgkmcnt(6)
	v_pk_mul_f32 v[8:9], v[118:119], v[126:127] op_sel_hi:[1,0]
	v_pk_mul_f32 v[10:11], v[120:121], v[126:127] op_sel_hi:[1,0]
	ds_read_b128 v[74:77], v141 offset:2112
	ds_read_b32 v82, v142 offset:1344
	ds_read_b128 v[66:69], v141 offset:1600
	ds_read_b128 v[62:65], v141 offset:1344
	ds_read_b128 v[70:73], v141 offset:1856
	v_pk_mul_f32 v[16:17], v[0:1], v[110:111]
	v_pk_fma_f32 v[16:17], v[2:3], v[112:113], v[16:17]
	v_add_f32_e32 v18, v16, v17
	v_pk_mul_f32 v[20:21], v[0:1], v[100:101]
	v_pk_fma_f32 v[4:5], v[0:1], v[106:107], v[8:9]
	v_add_f32_dpp v18, v18, v18 quad_perm:[1,0,3,2] row_mask:0xf bank_mask:0xf bound_ctrl:1
	v_pk_fma_f32 v[20:21], v[2:3], v[102:103], v[20:21]
	v_add_f32_e32 v200, v20, v21
	v_add_f32_dpp v18, v18, v18 quad_perm:[2,3,0,1] row_mask:0xf bank_mask:0xf bound_ctrl:1
	ds_read_b128 v[78:81], v141 offset:2368
	v_pk_fma_f32 v[6:7], v[2:3], v[108:109], v[10:11]
	v_add_f32_dpp v18, v18, v18 row_half_mirror row_mask:0xf bank_mask:0xf bound_ctrl:1
	v_add_f32_dpp v200, v200, v200 row_ror:8 row_mask:0xf bank_mask:0xc bound_ctrl:1
	v_add_f32_dpp v200, v190, v190 row_ror:8 row_mask:0xf bank_mask:0x3 bound_ctrl:1
	v_add_f32_dpp v18, v18, v18 row_ror:8 row_mask:0xf bank_mask:0xf bound_ctrl:1
	v_pk_fma_f32 v[0:1], v[114:115], v[18:19], v[4:5] op_sel_hi:[1,0,1] neg_lo:[1,0,0] neg_hi:[1,0,0]
	v_pk_fma_f32 v[2:3], v[116:117], v[18:19], v[6:7] op_sel_hi:[1,0,1] neg_lo:[1,0,0] neg_hi:[1,0,0]
	s_waitcnt lgkmcnt(6)
	v_pk_mul_f32 v[8:9], v[52:53], v[60:61] op_sel_hi:[1,0]
	v_pk_mul_f32 v[10:11], v[54:55], v[60:61] op_sel_hi:[1,0]
	s_add_i32 s4, s4, 1
	s_mov_b32 s0, s6
	s_mov_b32 s6, s7
	s_mov_b32 s7, s25
	s_mov_b32 s25, s0
	v_mov_b32_e32 v139, v141
	v_mov_b32_e32 v140, v142
	v_add_u32_e32 v141, s7, v24
	v_add_u32_e32 v142, s7, v25
	v_add_u32_e32 v143, s7, v26
	v_add_u32_e32 v35, s7, v27
	ds_read_b128 v[96:99], v139 offset:3456
	ds_read_b32 v104, v140 offset:2688
	ds_read_b128 v[88:91], v139 offset:2944
	ds_read_b128 v[84:87], v139 offset:2688
	ds_read_b128 v[92:95], v139 offset:3200
	v_pk_mul_f32 v[16:17], v[0:1], v[44:45]
	v_pk_fma_f32 v[16:17], v[2:3], v[46:47], v[16:17]
	v_add_f32_e32 v18, v16, v17
	v_pk_mul_f32 v[20:21], v[0:1], v[122:123]
	v_pk_fma_f32 v[4:5], v[0:1], v[40:41], v[8:9]
	v_add_f32_dpp v18, v18, v18 quad_perm:[1,0,3,2] row_mask:0xf bank_mask:0xf bound_ctrl:1
	v_pk_fma_f32 v[20:21], v[2:3], v[124:125], v[20:21]
	v_add_f32_e32 v201, v20, v21
	v_add_f32_dpp v18, v18, v18 quad_perm:[2,3,0,1] row_mask:0xf bank_mask:0xf bound_ctrl:1
	ds_read_b128 v[100:103], v139 offset:3712
	v_pk_fma_f32 v[6:7], v[2:3], v[42:43], v[10:11]
	v_add_f32_dpp v18, v18, v18 row_half_mirror row_mask:0xf bank_mask:0xf bound_ctrl:1
	v_add_f32_dpp v201, v201, v201 row_ror:8 row_mask:0xf bank_mask:0xc bound_ctrl:1
	v_add_f32_dpp v201, v191, v191 row_ror:8 row_mask:0xf bank_mask:0x3 bound_ctrl:1
	v_add_f32_dpp v18, v18, v18 row_ror:8 row_mask:0xf bank_mask:0xf bound_ctrl:1
	v_pk_fma_f32 v[0:1], v[48:49], v[18:19], v[4:5] op_sel_hi:[1,0,1] neg_lo:[1,0,0] neg_hi:[1,0,0]
	v_pk_fma_f32 v[2:3], v[50:51], v[18:19], v[6:7] op_sel_hi:[1,0,1] neg_lo:[1,0,0] neg_hi:[1,0,0]
	s_waitcnt lgkmcnt(6)
	v_pk_mul_f32 v[8:9], v[74:75], v[82:83] op_sel_hi:[1,0]
	v_pk_mul_f32 v[10:11], v[76:77], v[82:83] op_sel_hi:[1,0]
	ds_read_b128 v[118:121], v139 offset:4800
	ds_read_b32 v126, v140 offset:4032
	ds_read_b128 v[110:113], v139 offset:4288
	ds_read_b128 v[106:109], v139 offset:4032
	ds_read_b128 v[114:117], v139 offset:4544
	ds_read_b128 v[122:125], v139 offset:5056
	v_pk_mul_f32 v[16:17], v[0:1], v[66:67]
	v_pk_fma_f32 v[16:17], v[2:3], v[68:69], v[16:17]
	v_add_f32_e32 v18, v16, v17
	v_pk_mul_f32 v[20:21], v[0:1], v[56:57]
	v_pk_fma_f32 v[4:5], v[0:1], v[62:63], v[8:9]
	v_add_f32_dpp v18, v18, v18 quad_perm:[1,0,3,2] row_mask:0xf bank_mask:0xf bound_ctrl:1
	v_pk_fma_f32 v[20:21], v[2:3], v[58:59], v[20:21]
	v_add_f32_e32 v12, v20, v21
	v_add_f32_dpp v18, v18, v18 quad_perm:[2,3,0,1] row_mask:0xf bank_mask:0xf bound_ctrl:1
	v_add_f32_dpp v196, v196, v196 row_half_mirror row_mask:0xf bank_mask:0xa bound_ctrl:1
	v_pk_fma_f32 v[6:7], v[2:3], v[64:65], v[10:11]
	v_add_f32_dpp v18, v18, v18 row_half_mirror row_mask:0xf bank_mask:0xf bound_ctrl:1
	v_add_f32_dpp v196, v192, v192 row_half_mirror row_mask:0xf bank_mask:0x5 bound_ctrl:1
	v_add_f32_dpp v197, v197, v197 row_half_mirror row_mask:0xf bank_mask:0xa bound_ctrl:1
	v_add_f32_dpp v18, v18, v18 row_ror:8 row_mask:0xf bank_mask:0xf bound_ctrl:1
	v_pk_fma_f32 v[0:1], v[70:71], v[18:19], v[4:5] op_sel_hi:[1,0,1] neg_lo:[1,0,0] neg_hi:[1,0,0]
	v_pk_fma_f32 v[2:3], v[72:73], v[18:19], v[6:7] op_sel_hi:[1,0,1] neg_lo:[1,0,0] neg_hi:[1,0,0]
	s_waitcnt lgkmcnt(6)
	v_pk_mul_f32 v[8:9], v[96:97], v[104:105] op_sel_hi:[1,0]
	v_pk_mul_f32 v[10:11], v[98:99], v[104:105] op_sel_hi:[1,0]
	ds_read_b128 v[52:55], v139 offset:6144
	ds_read_b32 v60, v140 offset:5376
	ds_read_b128 v[44:47], v139 offset:5632
	ds_read_b128 v[40:43], v139 offset:5376
	ds_read_b128 v[48:51], v139 offset:5888
	ds_read_b128 v[56:59], v139 offset:6400
	v_pk_mul_f32 v[16:17], v[0:1], v[88:89]
	v_pk_fma_f32 v[16:17], v[2:3], v[90:91], v[16:17]
	v_add_f32_e32 v18, v16, v17
	v_pk_mul_f32 v[20:21], v[0:1], v[78:79]
	v_pk_fma_f32 v[4:5], v[0:1], v[84:85], v[8:9]
	v_add_f32_dpp v18, v18, v18 quad_perm:[1,0,3,2] row_mask:0xf bank_mask:0xf bound_ctrl:1
	v_pk_fma_f32 v[20:21], v[2:3], v[80:81], v[20:21]
	v_add_f32_e32 v13, v20, v21
	v_add_f32_dpp v18, v18, v18 quad_perm:[2,3,0,1] row_mask:0xf bank_mask:0xf bound_ctrl:1
	v_add_f32_dpp v197, v193, v193 row_half_mirror row_mask:0xf bank_mask:0x5 bound_ctrl:1
	v_pk_fma_f32 v[6:7], v[2:3], v[86:87], v[10:11]
	v_add_f32_dpp v18, v18, v18 row_half_mirror row_mask:0xf bank_mask:0xf bound_ctrl:1
	v_add_f32_dpp v200, v200, v200 row_half_mirror row_mask:0xf bank_mask:0xa bound_ctrl:1
	v_add_f32_dpp v200, v194, v194 row_half_mirror row_mask:0xf bank_mask:0x5 bound_ctrl:1
	v_add_f32_dpp v18, v18, v18 row_ror:8 row_mask:0xf bank_mask:0xf bound_ctrl:1
	v_pk_fma_f32 v[0:1], v[92:93], v[18:19], v[4:5] op_sel_hi:[1,0,1] neg_lo:[1,0,0] neg_hi:[1,0,0]
	v_pk_fma_f32 v[2:3], v[94:95], v[18:19], v[6:7] op_sel_hi:[1,0,1] neg_lo:[1,0,0] neg_hi:[1,0,0]
	s_waitcnt lgkmcnt(6)
	v_pk_mul_f32 v[8:9], v[118:119], v[126:127] op_sel_hi:[1,0]
	v_pk_mul_f32 v[10:11], v[120:121], v[126:127] op_sel_hi:[1,0]
	ds_read_b128 v[74:77], v139 offset:7488
	ds_read_b32 v82, v140 offset:6720
	ds_read_b128 v[66:69], v139 offset:6976
	ds_read_b128 v[62:65], v139 offset:6720
	ds_read_b128 v[70:73], v139 offset:7232
	ds_read_b128 v[78:81], v139 offset:7744
	v_pk_mul_f32 v[16:17], v[0:1], v[110:111]
	v_pk_fma_f32 v[16:17], v[2:3], v[112:113], v[16:17]
	v_add_f32_e32 v18, v16, v17
	v_pk_mul_f32 v[20:21], v[0:1], v[100:101]
	v_pk_fma_f32 v[4:5], v[0:1], v[106:107], v[8:9]
	v_add_f32_dpp v18, v18, v18 quad_perm:[1,0,3,2] row_mask:0xf bank_mask:0xf bound_ctrl:1
	v_pk_fma_f32 v[20:21], v[2:3], v[102:103], v[20:21]
	v_add_f32_e32 v14, v20, v21
	v_add_f32_dpp v18, v18, v18 quad_perm:[2,3,0,1] row_mask:0xf bank_mask:0xf bound_ctrl:1
	v_add_f32_dpp v201, v201, v201 row_half_mirror row_mask:0xf bank_mask:0xa bound_ctrl:1
	v_pk_fma_f32 v[6:7], v[2:3], v[108:109], v[10:11]
	v_add_f32_dpp v18, v18, v18 row_half_mirror row_mask:0xf bank_mask:0xf bound_ctrl:1
	v_add_f32_dpp v201, v195, v195 row_half_mirror row_mask:0xf bank_mask:0x5 bound_ctrl:1
	v_cndmask_b32_e64 v22, v196, v200, s[36:37]
	v_add_f32_dpp v18, v18, v18 row_ror:8 row_mask:0xf bank_mask:0xf bound_ctrl:1
	v_pk_fma_f32 v[0:1], v[114:115], v[18:19], v[4:5] op_sel_hi:[1,0,1] neg_lo:[1,0,0] neg_hi:[1,0,0]
	v_pk_fma_f32 v[2:3], v[116:117], v[18:19], v[6:7] op_sel_hi:[1,0,1] neg_lo:[1,0,0] neg_hi:[1,0,0]
	s_waitcnt lgkmcnt(6)
	v_pk_mul_f32 v[8:9], v[52:53], v[60:61] op_sel_hi:[1,0]
	v_pk_mul_f32 v[10:11], v[54:55], v[60:61] op_sel_hi:[1,0]
	ds_read_b128 v[96:99], v139 offset:8832
	ds_read_b32 v104, v140 offset:8064
	ds_read_b128 v[88:91], v139 offset:8320
	ds_read_b128 v[84:87], v139 offset:8064
	ds_read_b128 v[92:95], v139 offset:8576
	ds_read_b128 v[100:103], v139 offset:9088
	v_pk_mul_f32 v[16:17], v[0:1], v[44:45]
	v_pk_fma_f32 v[16:17], v[2:3], v[46:47], v[16:17]
	v_add_f32_e32 v18, v16, v17
	v_pk_mul_f32 v[20:21], v[0:1], v[122:123]
	v_pk_fma_f32 v[4:5], v[0:1], v[40:41], v[8:9]
	v_add_f32_dpp v18, v18, v18 quad_perm:[1,0,3,2] row_mask:0xf bank_mask:0xf bound_ctrl:1
	v_pk_fma_f32 v[20:21], v[2:3], v[124:125], v[20:21]
	v_add_f32_e32 v15, v20, v21
	v_add_f32_dpp v18, v18, v18 quad_perm:[2,3,0,1] row_mask:0xf bank_mask:0xf bound_ctrl:1
	v_cndmask_b32_e64 v202, v200, v196, s[36:37]
	v_pk_fma_f32 v[6:7], v[2:3], v[42:43], v[10:11]
	v_add_f32_dpp v18, v18, v18 row_half_mirror row_mask:0xf bank_mask:0xf bound_ctrl:1
	v_add_f32_dpp v200, v202, v22 quad_perm:[2,3,0,1] row_mask:0xf bank_mask:0xf bound_ctrl:1
	v_cndmask_b32_e64 v203, v197, v201, s[36:37]
	v_add_f32_dpp v18, v18, v18 row_ror:8 row_mask:0xf bank_mask:0xf bound_ctrl:1
	v_pk_fma_f32 v[0:1], v[48:49], v[18:19], v[4:5] op_sel_hi:[1,0,1] neg_lo:[1,0,0] neg_hi:[1,0,0]
	v_pk_fma_f32 v[2:3], v[50:51], v[18:19], v[6:7] op_sel_hi:[1,0,1] neg_lo:[1,0,0] neg_hi:[1,0,0]
	s_waitcnt lgkmcnt(6)
	v_pk_mul_f32 v[8:9], v[74:75], v[82:83] op_sel_hi:[1,0]
	v_pk_mul_f32 v[10:11], v[76:77], v[82:83] op_sel_hi:[1,0]
	ds_read_b128 v[118:121], v139 offset:10176
	ds_read_b32 v126, v140 offset:9408
	ds_read_b128 v[110:113], v139 offset:9664
	ds_read_b128 v[106:109], v139 offset:9408
	ds_read_b128 v[114:117], v139 offset:9920
	ds_read_b128 v[122:125], v139 offset:10432
	v_pk_mul_f32 v[16:17], v[0:1], v[66:67]
	v_pk_fma_f32 v[16:17], v[2:3], v[68:69], v[16:17]
	v_add_f32_e32 v18, v16, v17
	v_pk_mul_f32 v[20:21], v[0:1], v[56:57]
	v_pk_fma_f32 v[4:5], v[0:1], v[62:63], v[8:9]
	v_add_f32_dpp v18, v18, v18 quad_perm:[1,0,3,2] row_mask:0xf bank_mask:0xf bound_ctrl:1
	v_pk_fma_f32 v[20:21], v[2:3], v[58:59], v[20:21]
	v_add_f32_e32 v188, v20, v21
	v_add_f32_dpp v18, v18, v18 quad_perm:[2,3,0,1] row_mask:0xf bank_mask:0xf bound_ctrl:1
	v_cndmask_b32_e64 v202, v201, v197, s[36:37]
	v_pk_fma_f32 v[6:7], v[2:3], v[64:65], v[10:11]
	v_add_f32_dpp v18, v18, v18 row_half_mirror row_mask:0xf bank_mask:0xf bound_ctrl:1
	v_add_f32_dpp v201, v202, v203 quad_perm:[2,3,0,1] row_mask:0xf bank_mask:0xf bound_ctrl:1
	v_cndmask_b32_e64 v22, v200, v201, s[38:39]
	v_add_f32_dpp v18, v18, v18 row_ror:8 row_mask:0xf bank_mask:0xf bound_ctrl:1
	v_pk_fma_f32 v[0:1], v[70:71], v[18:19], v[4:5] op_sel_hi:[1,0,1] neg_lo:[1,0,0] neg_hi:[1,0,0]
	v_pk_fma_f32 v[2:3], v[72:73], v[18:19], v[6:7] op_sel_hi:[1,0,1] neg_lo:[1,0,0] neg_hi:[1,0,0]
	s_waitcnt lgkmcnt(6)
	v_pk_mul_f32 v[8:9], v[96:97], v[104:105] op_sel_hi:[1,0]
	v_pk_mul_f32 v[10:11], v[98:99], v[104:105] op_sel_hi:[1,0]
	ds_read_b128 v[52:55], v139 offset:11520
	ds_read_b32 v60, v140 offset:10752
	ds_read_b128 v[44:47], v139 offset:11008
	ds_read_b128 v[40:43], v139 offset:10752
	ds_read_b128 v[48:51], v139 offset:11264
	v_pk_mul_f32 v[16:17], v[0:1], v[88:89]
	v_pk_fma_f32 v[16:17], v[2:3], v[90:91], v[16:17]
	v_add_f32_e32 v18, v16, v17
	v_pk_mul_f32 v[20:21], v[0:1], v[78:79]
	v_pk_fma_f32 v[4:5], v[0:1], v[84:85], v[8:9]
	v_add_f32_dpp v18, v18, v18 quad_perm:[1,0,3,2] row_mask:0xf bank_mask:0xf bound_ctrl:1
	v_pk_fma_f32 v[20:21], v[2:3], v[80:81], v[20:21]
	v_add_f32_e32 v189, v20, v21
	v_add_f32_dpp v18, v18, v18 quad_perm:[2,3,0,1] row_mask:0xf bank_mask:0xf bound_ctrl:1
	v_cndmask_b32_e64 v202, v201, v200, s[38:39]
	v_pk_fma_f32 v[6:7], v[2:3], v[86:87], v[10:11]
	v_add_f32_dpp v18, v18, v18 row_half_mirror row_mask:0xf bank_mask:0xf bound_ctrl:1
	v_add_f32_dpp v23, v202, v22 quad_perm:[1,0,3,2] row_mask:0xf bank_mask:0xf bound_ctrl:1
	ds_read_b128 v[56:59], v139 offset:11776
	v_add_f32_dpp v18, v18, v18 row_ror:8 row_mask:0xf bank_mask:0xf bound_ctrl:1
	v_pk_fma_f32 v[0:1], v[92:93], v[18:19], v[4:5] op_sel_hi:[1,0,1] neg_lo:[1,0,0] neg_hi:[1,0,0]
	v_pk_fma_f32 v[2:3], v[94:95], v[18:19], v[6:7] op_sel_hi:[1,0,1] neg_lo:[1,0,0] neg_hi:[1,0,0]
	s_waitcnt lgkmcnt(6)
	v_pk_mul_f32 v[8:9], v[118:119], v[126:127] op_sel_hi:[1,0]
	v_pk_mul_f32 v[10:11], v[120:121], v[126:127] op_sel_hi:[1,0]
	s_cmp_eq_u32 s4, 0
	s_cbranch_scc1 .Lscan_noy1
	global_store_dword v138, v23, s[96:97]
	v_add_u32_e32 v138, s90, v138

.Lscan_wd_1:
	ds_write_b128 v143, v[168:171]
	ds_write_b128 v143, v[172:175] offset:256
	ds_write_b128 v143, v[176:179] offset:512
	ds_write_b128 v143, v[180:183] offset:768
	ds_write_b128 v143, v[184:187] offset:1024
	ds_write_b32 v35, v167
	ds_read_b128 v[74:77], v139 offset:18240
	ds_read_b32 v82, v140 offset:17472
	ds_read_b128 v[66:69], v139 offset:17728
	ds_read_b128 v[62:65], v139 offset:17472
	ds_read_b128 v[70:73], v139 offset:17984
	v_pk_mul_f32 v[16:17], v[0:1], v[110:111]
	v_pk_fma_f32 v[16:17], v[2:3], v[112:113], v[16:17]
	v_add_f32_e32 v18, v16, v17
	v_pk_mul_f32 v[20:21], v[0:1], v[100:101]
	v_pk_fma_f32 v[4:5], v[0:1], v[106:107], v[8:9]
	v_add_f32_dpp v18, v18, v18 quad_perm:[1,0,3,2] row_mask:0xf bank_mask:0xf bound_ctrl:1
	v_pk_fma_f32 v[20:21], v[2:3], v[102:103], v[20:21]
	v_add_f32_e32 v194, v20, v21
	v_add_f32_dpp v18, v18, v18 quad_perm:[2,3,0,1] row_mask:0xf bank_mask:0xf bound_ctrl:1
	ds_read_b128 v[78:81], v139 offset:18496
	v_pk_fma_f32 v[6:7], v[2:3], v[108:109], v[10:11]
	v_add_f32_dpp v18, v18, v18 row_half_mirror row_mask:0xf bank_mask:0xf bound_ctrl:1
	v_add_f32_dpp v194, v194, v194 row_ror:8 row_mask:0xf bank_mask:0xc bound_ctrl:1
	v_add_f32_dpp v194, v14, v14 row_ror:8 row_mask:0xf bank_mask:0x3 bound_ctrl:1
	v_add_f32_dpp v18, v18, v18 row_ror:8 row_mask:0xf bank_mask:0xf bound_ctrl:1
	v_pk_fma_f32 v[0:1], v[114:115], v[18:19], v[4:5] op_sel_hi:[1,0,1] neg_lo:[1,0,0] neg_hi:[1,0,0]
	v_pk_fma_f32 v[2:3], v[116:117], v[18:19], v[6:7] op_sel_hi:[1,0,1] neg_lo:[1,0,0] neg_hi:[1,0,0]
	s_waitcnt lgkmcnt(6)
	v_pk_mul_f32 v[8:9], v[52:53], v[60:61] op_sel_hi:[1,0]
	v_pk_mul_f32 v[10:11], v[54:55], v[60:61] op_sel_hi:[1,0]
	ds_read_b128 v[96:99], v139 offset:19584
	ds_read_b32 v104, v140 offset:18816
	ds_read_b128 v[88:91], v139 offset:19072
	ds_read_b128 v[84:87], v139 offset:18816
	ds_read_b128 v[92:95], v139 offset:19328
	v_pk_mul_f32 v[16:17], v[0:1], v[44:45]
	v_pk_fma_f32 v[16:17], v[2:3], v[46:47], v[16:17]
	v_add_f32_e32 v18, v16, v17
	v_pk_mul_f32 v[20:21], v[0:1], v[122:123]
	v_pk_fma_f32 v[4:5], v[0:1], v[40:41], v[8:9]
	v_add_f32_dpp v18, v18, v18 quad_perm:[1,0,3,2] row_mask:0xf bank_mask:0xf bound_ctrl:1
	v_pk_fma_f32 v[20:21], v[2:3], v[124:125], v[20:21]
	v_add_f32_e32 v195, v20, v21
	v_add_f32_dpp v18, v18, v18 quad_perm:[2,3,0,1] row_mask:0xf bank_mask:0xf bound_ctrl:1
	ds_read_b128 v[100:103], v139 offset:19840
	v_pk_fma_f32 v[6:7], v[2:3], v[42:43], v[10:11]
	v_add_f32_dpp v18, v18, v18 row_half_mirror row_mask:0xf bank_mask:0xf bound_ctrl:1
	v_add_f32_dpp v195, v195, v195 row_ror:8 row_mask:0xf bank_mask:0xc bound_ctrl:1
	v_add_f32_dpp v195, v15, v15 row_ror:8 row_mask:0xf bank_mask:0x3 bound_ctrl:1
	v_add_f32_dpp v18, v18, v18 row_ror:8 row_mask:0xf bank_mask:0xf bound_ctrl:1
	v_pk_fma_f32 v[0:1], v[48:49], v[18:19], v[4:5] op_sel_hi:[1,0,1] neg_lo:[1,0,0] neg_hi:[1,0,0]
	v_pk_fma_f32 v[2:3], v[50:51], v[18:19], v[6:7] op_sel_hi:[1,0,1] neg_lo:[1,0,0] neg_hi:[1,0,0]
	s_waitcnt lgkmcnt(6)
	s_barrier
	s_add_i32 s0, s4, 3
	s_cmp_lt_u32 s0, s5
	s_cbranch_scc0 .Lscan_nold1
	s_mul_i32 s92, s0, s90
	v_add_u32_e32 v132, s92, v28
	v_add_u32_e32 v133, s92, v29
	v_add_u32_e32 v134, s92, v30
	v_add_u32_e32 v135, s92, v31
	v_add_u32_e32 v136, s92, v32
	v_add_u32_e32 v137, s92, v33
	global_load_dwordx4 v[168:171], v132, s[96:97]
	global_load_dwordx4 v[172:175], v133, s[96:97]
	global_load_dwordx4 v[176:179], v134, s[96:97]
	global_load_dwordx4 v[180:183], v135, s[96:97]
	global_load_dwordx4 v[184:187], v136, s[96:97]
	global_load_dword v167, v137, s[96:97]
.Lscan_nold1:
	v_pk_mul_f32 v[8:9], v[74:75], v[82:83] op_sel_hi:[1,0]
	v_pk_mul_f32 v[10:11], v[76:77], v[82:83] op_sel_hi:[1,0]
	ds_read_b128 v[118:121], v139 offset:20928
	ds_read_b32 v126, v140 offset:20160
	ds_read_b128 v[110:113], v139 offset:20416
	ds_read_b128 v[106:109], v139 offset:20160
	ds_read_b128 v[114:117], v139 offset:20672
	v_pk_mul_f32 v[16:17], v[0:1], v[66:67]
	v_pk_fma_f32 v[16:17], v[2:3], v[68:69], v[16:17]
	v_add_f32_e32 v18, v16, v17
	v_pk_mul_f32 v[20:21], v[0:1], v[56:57]
	v_pk_fma_f32 v[4:5], v[0:1], v[62:63], v[8:9]
	v_add_f32_dpp v18, v18, v18 quad_perm:[1,0,3,2] row_mask:0xf bank_mask:0xf bound_ctrl:1
	v_pk_fma_f32 v[20:21], v[2:3], v[58:59], v[20:21]
	v_add_f32_e32 v196, v20, v21
	v_add_f32_dpp v18, v18, v18 quad_perm:[2,3,0,1] row_mask:0xf bank_mask:0xf bound_ctrl:1
	ds_read_b128 v[122:125], v139 offset:21184
	v_pk_fma_f32 v[6:7], v[2:3], v[64:65], v[10:11]
	v_add_f32_dpp v18, v18, v18 row_half_mirror row_mask:0xf bank_mask:0xf bound_ctrl:1
	v_add_f32_dpp v196, v196, v196 row_ror:8 row_mask:0xf bank_mask:0xc bound_ctrl:1
	v_add_f32_dpp v196, v188, v188 row_ror:8 row_mask:0xf bank_mask:0x3 bound_ctrl:1
	v_add_f32_dpp v18, v18, v18 row_ror:8 row_mask:0xf bank_mask:0xf bound_ctrl:1
	v_pk_fma_f32 v[0:1], v[70:71], v[18:19], v[4:5] op_sel_hi:[1,0,1] neg_lo:[1,0,0] neg_hi:[1,0,0]
	v_pk_fma_f32 v[2:3], v[72:73], v[18:19], v[6:7] op_sel_hi:[1,0,1] neg_lo:[1,0,0] neg_hi:[1,0,0]
	s_waitcnt lgkmcnt(6)
	v_pk_mul_f32 v[8:9], v[96:97], v[104:105] op_sel_hi:[1,0]
	v_pk_mul_f32 v[10:11], v[98:99], v[104:105] op_sel_hi:[1,0]
	ds_read_b128 v[52:55], v141 offset:768
	ds_read_b32 v60, v142 offset:0
	ds_read_b128 v[44:47], v141 offset:256
	ds_read_b128 v[40:43], v141 offset:0
	ds_read_b128 v[48:51], v141 offset:512
	v_pk_mul_f32 v[16:17], v[0:1], v[88:89]
	v_pk_fma_f32 v[16:17], v[2:3], v[90:91], v[16:17]
	v_add_f32_e32 v18, v16, v17
	v_pk_mul_f32 v[20:21], v[0:1], v[78:79]
	v_pk_fma_f32 v[4:5], v[0:1], v[84:85], v[8:9]
	v_add_f32_dpp v18, v18, v18 quad_perm:[1,0,3,2] row_mask:0xf bank_mask:0xf bound_ctrl:1
	v_pk_fma_f32 v[20:21], v[2:3], v[80:81], v[20:21]
	v_add_f32_e32 v197, v20, v21
	v_add_f32_dpp v18, v18, v18 quad_perm:[2,3,0,1] row_mask:0xf bank_mask:0xf bound_ctrl:1
	ds_read_b128 v[56:59], v141 offset:1024
	v_pk_fma_f32 v[6:7], v[2:3], v[86:87], v[10:11]
	v_add_f32_dpp v18, v18, v18 row_half_mirror row_mask:0xf bank_mask:0xf bound_ctrl:1
	v_add_f32_dpp v197, v197, v197 row_ror:8 row_mask:0xf bank_mask:0xc bound_ctrl:1
	v_add_f32_dpp v197, v189, v189 row_ror:8 row_mask:0xf bank_mask:0x3 bound_ctrl:1
	v_add_f32_dpp v18, v18, v18 row_ror:8 row_mask:0xf bank_mask:0xf bound_ctrl:1
	v_pk_fma_f32 v[0:1], v[92:93], v[18:19], v[4:5] op_sel_hi:[1,0,1] neg_lo:[1,0,0] neg_hi:[1,0,0]
	v_pk_fma_f32 v[2:3], v[94:95], v[18:19], v[6:7] op_sel_hi:[1,0,1] neg_lo:[1,0,0] neg_hi:[1,0,0]
	s_waitcnt lgkmcnt(6)
	v_pk_mul_f32 v[8:9], v[118:119], v[126:127] op_sel_hi:[1,0]
	v_pk_mul_f32 v[10:11], v[120:121], v[126:127] op_sel_hi:[1,0]
	ds_read_b128 v[74:77], v141 offset:2112
	ds_read_b32 v82, v142 offset:1344
	ds_read_b128 v[66:69], v141 offset:1600
	ds_read_b128 v[62:65], v141 offset:1344
	ds_read_b128 v[70:73], v141 offset:1856
	v_pk_mul_f32 v[16:17], v[0:1], v[110:111]
	v_pk_fma_f32 v[16:17], v[2:3], v[112:113], v[16:17]
	v_add_f32_e32 v18, v16, v17
	v_pk_mul_f32 v[20:21], v[0:1], v[100:101]
	v_pk_fma_f32 v[4:5], v[0:1], v[106:107], v[8:9]
	v_add_f32_dpp v18, v18, v18 quad_perm:[1,0,3,2] row_mask:0xf bank_mask:0xf bound_ctrl:1
	v_pk_fma_f32 v[20:21], v[2:3], v[102:103], v[20:21]
	v_add_f32_e32 v200, v20, v21
	v_add_f32_dpp v18, v18, v18 quad_perm:[2,3,0,1] row_mask:0xf bank_mask:0xf bound_ctrl:1
	ds_read_b128 v[78:81], v141 offset:2368
	v_pk_fma_f32 v[6:7], v[2:3], v[108:109], v[10:11]
	v_add_f32_dpp v18, v18, v18 row_half_mirror row_mask:0xf bank_mask:0xf bound_ctrl:1
	v_add_f32_dpp v200, v200, v200 row_ror:8 row_mask:0xf bank_mask:0xc bound_ctrl:1
	v_add_f32_dpp v200, v190, v190 row_ror:8 row_mask:0xf bank_mask:0x3 bound_ctrl:1
	v_add_f32_dpp v18, v18, v18 row_ror:8 row_mask:0xf bank_mask:0xf bound_ctrl:1
	v_pk_fma_f32 v[0:1], v[114:115], v[18:19], v[4:5] op_sel_hi:[1,0,1] neg_lo:[1,0,0] neg_hi:[1,0,0]
	v_pk_fma_f32 v[2:3], v[116:117], v[18:19], v[6:7] op_sel_hi:[1,0,1] neg_lo:[1,0,0] neg_hi:[1,0,0]
	s_waitcnt lgkmcnt(6)
	v_pk_mul_f32 v[8:9], v[52:53], v[60:61] op_sel_hi:[1,0]
	v_pk_mul_f32 v[10:11], v[54:55], v[60:61] op_sel_hi:[1,0]
	s_add_i32 s4, s4, 1
	s_mov_b32 s0, s6
	s_mov_b32 s6, s7
	s_mov_b32 s7, s25
	s_mov_b32 s25, s0
	v_mov_b32_e32 v139, v141
	v_mov_b32_e32 v140, v142
	v_add_u32_e32 v141, s7, v24
	v_add_u32_e32 v142, s7, v25
	v_add_u32_e32 v143, s7, v26
	v_add_u32_e32 v35, s7, v27
	s_cmp_lt_u32 s4, s5
	s_cbranch_scc1 .Lscan_chunk
	v_mul_f32_e32 v201, v0, v122
	v_fmac_f32_e32 v201, v1, v123
	v_fmac_f32_e32 v201, v2, v124
	v_fmac_f32_e32 v201, v3, v125
	s_nop 1
	v_add_f32_dpp v201, v201, v201 row_ror:8 row_mask:0xf bank_mask:0xc bound_ctrl:1
	v_add_f32_dpp v201, v191, v191 row_ror:8 row_mask:0xf bank_mask:0x3 bound_ctrl:1
	s_nop 1
	v_add_f32_dpp v196, v196, v196 row_half_mirror row_mask:0xf bank_mask:0xa bound_ctrl:1
	v_add_f32_dpp v196, v192, v192 row_half_mirror row_mask:0xf bank_mask:0x5 bound_ctrl:1
	v_add_f32_dpp v197, v197, v197 row_half_mirror row_mask:0xf bank_mask:0xa bound_ctrl:1
	v_add_f32_dpp v197, v193, v193 row_half_mirror row_mask:0xf bank_mask:0x5 bound_ctrl:1
	v_add_f32_dpp v200, v200, v200 row_half_mirror row_mask:0xf bank_mask:0xa bound_ctrl:1
	v_add_f32_dpp v200, v194, v194 row_half_mirror row_mask:0xf bank_mask:0x5 bound_ctrl:1
	v_add_f32_dpp v201, v201, v201 row_half_mirror row_mask:0xf bank_mask:0xa bound_ctrl:1
	v_add_f32_dpp v201, v195, v195 row_half_mirror row_mask:0xf bank_mask:0x5 bound_ctrl:1
	s_nop 1
	v_cndmask_b32_e64 v22, v196, v200, s[36:37]
	v_cndmask_b32_e64 v202, v200, v196, s[36:37]
	s_nop 1
	v_add_f32_dpp v200, v202, v22 quad_perm:[2,3,0,1] row_mask:0xf bank_mask:0xf bound_ctrl:1
	v_cndmask_b32_e64 v203, v197, v201, s[36:37]
	v_cndmask_b32_e64 v202, v201, v197, s[36:37]
	s_nop 1
	v_add_f32_dpp v201, v202, v203 quad_perm:[2,3,0,1] row_mask:0xf bank_mask:0xf bound_ctrl:1
	v_cndmask_b32_e64 v22, v200, v201, s[38:39]
	v_cndmask_b32_e64 v202, v201, v200, s[38:39]
	s_nop 1
	v_add_f32_dpp v23, v202, v22 quad_perm:[1,0,3,2] row_mask:0xf bank_mask:0xf bound_ctrl:1
	global_store_dword v138, v23, s[96:97]
	s_cmp_eq_u32 s28, 0
	s_cbranch_scc1 .Lscan_done
	v_readlane_b32 s0, v254, 57
	v_readlane_b32 s1, v254, 58
	s_nop 4
	global_store_dwordx4 v39, v[0:3], s[0:1]
